# split-phase flat barrier (arrive after GLA pre-pass, wait before recurrence) + half the WGs run GLA-sample after the prompt recurrence
# baseline (speedup 1.0000x reference)
; __device__ __forceinline__ float bflo(unsigned w) { return __uint_as_float(w << 16); }
; __device__ __forceinline__ void swa_prompt_unit(const Args& a, unsigned char* lds, int unit, int tid) {
;     const int lane = tid & 63, wave = tid >> 6, r16 = lane & 15, q4 = lane >> 4;
;     const int kvh = unit & 3, blk = (unit >> 2) & 15, b = unit >> 6;
;     unsigned char* KL = lds; unsigned char* VTL = lds + 36864;
;     const bf16_t* Z = (const bf16_t*)(a.ws + WS_Z); bf16_t* OCAT = (bf16_t*)(a.ws + WS_OCAT); const f32x2* ROPE = (const f32x2*)(a.ws + WS_ROPE);
; #pragma unroll
;     for (int it = 0; it < 4; ++it) { const int e = tid + it * 512, j = e >> 3, c = e & 7; const int kpos = (blk - 1) * 128 + j; const bool valid = kpos >= 0;
;         const size_t row = (size_t)b * 2048 + (valid ? kpos : 0);
;         u32x4 raw = (u32x4){0u, 0u, 0u, 0u}, rawv = (u32x4){0u, 0u, 0u, 0u}; float kf[8];
;         if (valid) { raw = *(const u32x4*)(Z + row * DINP + ZKS + kvh * 64 + c * 8); rawv = *(const u32x4*)(Z + row * DINP + ZVS + kvh * 64 + c * 8); }
;         kf[0] = bflo(raw.x); kf[1] = bfhi(raw.x); kf[2] = bflo(raw.y); kf[3] = bfhi(raw.y); kf[4] = bflo(raw.z); kf[5] = bfhi(raw.z); kf[6] = bflo(raw.w); kf[7] = bfhi(raw.w);
;         if (c < 2 && valid) { const u32x4 pr = *(const u32x4*)(Z + row * DINP + ZKS + kvh * 64 + (c ^ 1) * 8);
;             float pf[8]; pf[0] = bflo(pr.x); pf[1] = bfhi(pr.x); pf[2] = bflo(pr.y); pf[3] = bfhi(pr.y); pf[4] = bflo(pr.z); pf[5] = bfhi(pr.z); pf[6] = bflo(pr.w); pf[7] = bfhi(pr.w);
;             const f32x2* rp = ROPE + kpos * 8; const float sg = c == 0 ? -1.f : 1.f;
; #pragma unroll
;             for (int d = 0; d < 8; ++d) { const f32x2 cs = rp[d]; kf[d] = kf[d] * cs.x + sg * pf[d] * cs.y; }
;             raw.x = cvt_pk_bf16(kf[0], kf[1]); raw.y = cvt_pk_bf16(kf[2], kf[3]); raw.z = cvt_pk_bf16(kf[4], kf[5]); raw.w = cvt_pk_bf16(kf[6], kf[7]);
;             kf[0] = bflo(raw.x); kf[1] = bfhi(raw.x); kf[2] = bflo(raw.y); kf[3] = bfhi(raw.y); kf[4] = bflo(raw.z); kf[5] = bfhi(raw.z); kf[6] = bflo(raw.w); kf[7] = bfhi(raw.w); }
;         *(u32x4*)(KL + j * 144 + c * 16) = raw;
;         bf16_t* vt = (bf16_t*)VTL + (c * 8) * 264 + j;
;         vt[0 * 264] = (bf16_t)(rawv.x & 0xffffu); vt[1 * 264] = (bf16_t)(rawv.x >> 16); vt[2 * 264] = (bf16_t)(rawv.y & 0xffffu); vt[3 * 264] = (bf16_t)(rawv.y >> 16);
.LBB0_255:
	s_bfe_u32 s100, s2, 0x10003
	s_waitcnt vmcnt(0)
	s_barrier
	v_cmp_eq_u32_e32 vcc, 0, v188
	s_and_saveexec_b64 s[0:1], vcc
	s_cbranch_execz .Lfa_done
	buffer_wbl2 sc1
	s_waitcnt vmcnt(0)
	v_mov_b32_e32 v252, 0
	v_mov_b32_e32 v253, 1
	s_add_u32 s4, s86, 0x23840
	s_addc_u32 s5, s87, 0
	global_atomic_add v252, v253, s[4:5]
.Lfa_done:
	s_or_b64 exec, exec, s[0:1]
	s_cmpk_gt_i32 s2, 0x1ff
	s_movk_i32 s0, 0x1ff
	s_cbranch_scc1 .LBB0_432
	v_writelane_b32 v249, s90, 37
	s_add_u32 s4, s86, 0xa0000
	s_addc_u32 s5, s87, 0
	v_writelane_b32 v249, s91, 38
	v_writelane_b32 v249, s88, 39
	v_and_b32_e32 v1, 7, v188
	v_lshl_add_u32 v2, v1, 4, 0
	v_writelane_b32 v249, s89, 40
	v_writelane_b32 v249, s4, 41
	s_movk_i32 s1, 0x1070
	v_add_u32_e32 v5, 0x600, v188
	v_writelane_b32 v249, s5, 42
	v_cmp_gt_u32_e64 s[4:5], 2, v1
	v_cmp_lt_u32_e64 s[6:7], 1, v1
	v_lshlrev_b32_e32 v74, 3, v1
	v_cmp_eq_u32_e64 s[8:9], 0, v1
	v_mad_u32_u24 v1, v1, s1, v2
	v_lshrrev_b32_e32 v75, 3, v188
	v_lshrrev_b32_e32 v83, 3, v89
	s_add_u32 s92, s84, 0x8400000
	v_lshrrev_b32_e32 v105, 3, v5
	v_lshl_add_u32 v77, v75, 1, v1
	v_lshl_add_u32 v93, v83, 1, v1
	s_addc_u32 s93, s85, 0
	v_lshl_add_u32 v106, v105, 1, v1
	v_bfe_u32 v1, v188, 6, 1
	v_lshlrev_b32_e32 v90, 3, v86
	v_add_u32_e32 v6, 0, v31
	v_mov_b32_e32 v0, 0
	v_mul_u32_u24_e32 v3, 0x90, v75
	v_mul_u32_u24_e32 v4, 0x90, v83
	v_cmp_lt_u32_e64 s[10:11], s0, v188
	s_add_u32 s90, s84, 0x8500000
	v_mul_u32_u24_e32 v5, 0x90, v105
	v_lshrrev_b32_e32 v92, 7, v188
	v_lshlrev_b32_e32 v107, 2, v1
	v_lshlrev_b32_e32 v108, 2, v86
	v_sub_u32_e32 v7, v6, v90
	v_mul_u32_u24_e32 v8, 0x90, v124
	s_movk_i32 s0, 0x210
	v_lshl_or_b32 v178, v1, 6, v124
	s_mov_b32 s3, 0xc600000
	v_mbcnt_lo_u32_b32 v1, -1, 0
	v_xor_b32_e32 v76, 8, v74
	s_mov_b32 s63, 0
	s_addc_u32 s91, s85, 0
	v_or_b32_e32 v104, 0x80, v75
	v_cmp_gt_u32_e64 s[12:13], 2, v86
	v_cmp_eq_u32_e64 s[14:15], 0, v86
	v_or_b32_e32 v109, 2, v108
	v_or_b32_e32 v110, 3, v108
	v_or_b32_e32 v111, 16, v108
	v_or_b32_e32 v112, 17, v108
	v_or_b32_e32 v113, 18, v108
	v_or_b32_e32 v114, 19, v108
	v_or_b32_e32 v115, 32, v108
	v_or_b32_e32 v116, 33, v108
	v_or_b32_e32 v117, 34, v108
	v_or_b32_e32 v118, 35, v108
	v_or_b32_e32 v119, 48, v108
	v_or_b32_e32 v120, 49, v108
	v_or_b32_e32 v121, 50, v108
	v_or_b32_e32 v122, 51, v108
	v_or_b32_e32 v123, 64, v108
	v_or_b32_e32 v129, 0x41, v108
	v_or_b32_e32 v130, 0x42, v108
	v_or_b32_e32 v131, 0x43, v108
	v_or_b32_e32 v132, 0x50, v108
	v_or_b32_e32 v133, 0x51, v108
	v_or_b32_e32 v134, 0x52, v108
	v_or_b32_e32 v135, 0x53, v108
	v_or_b32_e32 v136, 0x60, v108
	v_or_b32_e32 v137, 0x61, v108
	v_or_b32_e32 v138, 0x62, v108
	v_or_b32_e32 v139, 0x63, v108
	v_or_b32_e32 v140, 0x70, v108
	v_or_b32_e32 v141, 0x71, v108
	v_or_b32_e32 v142, 0x72, v108
	v_or_b32_e32 v143, 0x73, v108
	v_or_b32_e32 v144, 0x81, v108
	v_or_b32_e32 v145, 0x82, v108
	v_or_b32_e32 v146, 0x83, v108
	v_or_b32_e32 v147, 0x90, v108
	v_or_b32_e32 v149, 0x91, v108
	v_or_b32_e32 v150, 0x92, v108
	v_or_b32_e32 v152, 0x93, v108
	v_or_b32_e32 v153, 0xa0, v108
	v_or_b32_e32 v154, 0xa1, v108
	v_or_b32_e32 v155, 0xa2, v108
	v_or_b32_e32 v156, 0xa3, v108
	v_or_b32_e32 v157, 0xb0, v108
	v_or_b32_e32 v158, 0xb1, v108
	v_or_b32_e32 v159, 0xb2, v108
	v_or_b32_e32 v160, 0xb3, v108
	v_or_b32_e32 v161, 0xc0, v108
	v_or_b32_e32 v162, 0xc1, v108
	v_or_b32_e32 v163, 0xc2, v108
	v_or_b32_e32 v164, 0xc3, v108
	v_or_b32_e32 v165, 0xd0, v108
	v_or_b32_e32 v166, 0xd1, v108
	v_or_b32_e32 v167, 0xd2, v108
	v_or_b32_e32 v168, 0xd3, v108
	v_or_b32_e32 v169, 0xe0, v108
	v_or_b32_e32 v170, 0xe1, v108
	v_or_b32_e32 v171, 0xe2, v108
	v_or_b32_e32 v172, 0xe3, v108
	v_or_b32_e32 v173, 0xf0, v108
	v_or_b32_e32 v174, 0xf1, v108
	v_or_b32_e32 v175, 0xf2, v108
	v_or_b32_e32 v176, 0xf3, v108
	v_mad_u32_u24 v177, v124, s0, v7
	v_bitop3_b32 v78, v31, s3, 16 bitop3:0xde
	v_mov_b32_e32 v79, v0
	v_lshlrev_b32_e32 v179, 6, v92
	v_or_b32_e32 v80, 0x24a00040, v90
	v_mov_b32_e32 v81, v0
	v_and_b32_e32 v82, 48, v188
	s_movk_i32 s89, 0x5e00
	v_add_u32_e32 v180, v2, v4
	v_lshlrev_b32_e32 v94, 1, v74
	v_add_u32_e32 v181, v2, v5
	v_mbcnt_hi_u32_b32 v151, -1, v1
	s_mov_b64 s[80:81], 0x5e000
	v_add_u32_e32 v182, v2, v3
	v_mov_b32_e32 v183, 0x2f00000
	v_mov_b32_e32 v185, 0xc00000
	v_add_u32_e32 v187, v6, v8
	v_mov_b32_e32 v190, 0xff61b1e6
	s_mov_b32 s88, s2
	s_mov_b32 s94, s2
	s_branch .LBB0_258

; __device__ __forceinline__ void gla_sample_unit(const Args& a, unsigned char* lds, int unit, int tid) {
;     const int lane = tid & 63, wave = tid >> 6;
;     const int b = unit >> 2, h = unit & 3;
;     float* Q4 = (float*)lds;
;     float* KD4 = Q4 + 1024;
;     float* KI4 = KD4 + 1024;
;     float* DECS = KI4 + 1024;
;     float* AS = DECS + 256;
;     float* RED = AS + 16;
;     float* VS = RED + 16;
;     float* ORED = VS + 2048;
;     const bf16_t* Z = (const bf16_t*)(a.ws + WS_Z); bf16_t* OCAT = (bf16_t*)(a.ws + WS_OCAT);
;     const size_t row0 = (size_t)MP + b * 4;
;     if (tid < 256) { const int kcol = tid; float la[4];
; #pragma unroll
;         for (int t = 0; t < 4; ++t) la[t] = a.b_a[h * 256 + kcol];
; #pragma unroll
;         for (int r = 0; r < 16; ++r) { const float w = a.w_a2[r * 1024 + h * 256 + kcol];
; #pragma unroll
;             for (int t = 0; t < 4; ++t) la[t] += bf2f(Z[(row0 + t) * DINP + ZAG + r]) * w; }
;         float bb[4]; float c = 0.f;
; #pragma unroll
;         for (int t = 0; t < 4; ++t) { c += logsig16(la[t]); bb[t] = c; }
;         f32x4 qv, kd, ki;
; #pragma unroll
;         for (int t = 0; t < 4; ++t) { const float q = bf2f(Z[(row0 + t) * DINP + ZQG + h * 256 + kcol]), k = bf2f(Z[(row0 + t) * DINP + ZKG + h * 256 + kcol]);
;             qv[t] = q * __expf(bb[t]) * 0.0625f; ki[t] = k * __expf(-bb[t]); kd[t] = k * __expf(c - bb[t]); }
;         *(f32x4*)(Q4 + kcol * 4) = qv; *(f32x4*)(KD4 + kcol * 4) = kd; *(f32x4*)(KI4 + kcol * 4) = ki; DECS[kcol] = __expf(c);
;     } else { const int j = tid - 256, t = j >> 6, c = j & 63; const u32x4 raw = *(const u32x4*)(Z + (row0 + t) * DINP + ZVG + h * 512 + c * 8);
;         float* d = VS + t * 512 + c * 8; *(f32x4*)d = (f32x4){bflo(raw.x), bfhi(raw.x), bflo(raw.y), bfhi(raw.y)}; *(f32x4*)(d + 4) = (f32x4){bflo(raw.z), bfhi(raw.z), bflo(raw.w), bfhi(raw.w)}; }
;     __syncthreads();
;     { const int pair = tid >> 5, sub = tid & 31, t = pair >> 2, m = pair & 3; float s = 0.f;
; #pragma unroll
;       for (int i = 0; i < 8; ++i) { const int k = sub + 32 * i; s += Q4[k * 4 + t] * KI4[k * 4 + m]; }
; #pragma unroll
;       for (int o = 1; o < 32; o <<= 1) s += __shfl_xor(s, o);
;       if (sub == 0) AS[t * 4 + m] = (m <= t) ? s : 0.f; }
;     const int kq = tid >> 7, vc = (tid & 127) * 4;
;     f32x4 vr[4], o[4];
; #pragma unroll
.LBB0_382:
	s_cmp_eq_u32 s100, 2
	s_cbranch_scc1 .Lswap_p2
	v_mov_b32_e32 v251, v151
	v_mov_b32_e32 v252, v85
	v_mov_b32_e32 v253, v91
	v_mov_b32_e32 v254, v92
	v_mov_b32_e32 v255, v128
	s_branch .Lswap_p
.Lswap_p2:
	v_mov_b32_e32 v151, v147
	v_mov_b32_e32 v85, v149
	v_mov_b32_e32 v91, v182
	v_mov_b32_e32 v92, v254
	v_mov_b32_e32 v128, v255
.Lswap_p:
	v_add_u32_e32 v0, 0xffffff00, v188
	v_lshrrev_b32_e32 v94, 6, v0
	v_and_b32_e32 v2, 0x1f8, v91
	v_lshlrev_b32_e32 v0, 11, v94
	v_lshlrev_b32_e32 v1, 2, v2
	v_add3_u32 v134, 0, v0, v1
	v_and_b32_e32 v0, 31, v188
	v_lshlrev_b32_e32 v4, 2, v92
	v_lshlrev_b32_e32 v6, 4, v0
	v_add3_u32 v136, 0, v4, v6
	v_xor_b32_e32 v4, 1, v151
	v_cmp_lt_i32_e32 vcc, v4, v66
	s_movk_i32 s0, 0x100
	v_cmp_gt_u32_e64 s[4:5], s0, v188
	v_cndmask_b32_e32 v4, v151, v4, vcc
	v_lshlrev_b32_e32 v129, 2, v4
	v_xor_b32_e32 v4, 2, v151
	v_cmp_lt_i32_e32 vcc, v4, v66
	s_movk_i32 s0, 0xff
	v_lshlrev_b32_e32 v133, 2, v188
	v_cndmask_b32_e32 v4, v151, v4, vcc
	v_lshlrev_b32_e32 v130, 2, v4
	v_xor_b32_e32 v4, 4, v151
	v_cmp_lt_i32_e32 vcc, v4, v66
	v_lshl_add_u32 v138, v92, 4, 0
	v_cmp_lt_u32_e64 s[6:7], s0, v188
	v_cndmask_b32_e32 v4, v151, v4, vcc
	v_lshlrev_b32_e32 v131, 2, v4
	v_xor_b32_e32 v4, 8, v151
	v_bfe_u32 v3, v188, 5, 2
	v_cmp_lt_i32_e32 vcc, v4, v66
	v_cmp_eq_u32_e64 s[8:9], 0, v0
	v_and_b32_e32 v0, 0x1fc, v133
	v_mad_i32_i24 v141, v92, -12, v138
	s_movk_i32 s0, 0x1ffc
	v_lshlrev_b32_e32 v5, 2, v3
	v_cndmask_b32_e32 v4, v151, v4, vcc
	v_cmp_gt_u32_e64 s[10:11], v3, v92
	v_lshlrev_b32_e32 v96, 2, v0
	v_mad_u32_u24 v3, v92, s0, v141
	s_movk_i32 s0, 0xe800
	s_ashr_i32 s3, s2, 31
	v_lshlrev_b32_e32 v132, 2, v4
	v_add_u32_e32 v210, v3, v96
	v_mad_i32_i24 v3, v92, s0, v3
	v_and_b32_e32 v4, 0x7f, v188
	s_lshl_b64 s[0:1], s[2:3], 19
	v_add3_u32 v137, 0, v5, v6
	v_add_u32_e32 v139, v138, v5
	v_lshlrev_b32_e32 v100, 4, v4
	v_lshl_or_b32 v4, v92, 11, s0
	v_mov_b32_e32 v5, s1
	v_readlane_b32 s0, v249, 21
	v_readlane_b32 s16, v249, 5
	v_readlane_b32 s1, v249, 22
	v_mov_b32_e32 v97, 0
	v_lshl_add_u32 v135, v188, 4, 0
	v_mul_i32_i24_e32 v1, -12, v188
	v_mul_i32_i24_e32 v6, 0xfffff808, v92
	v_readlane_b32 s17, v249, 6
	v_readlane_b32 s18, v249, 7
	v_readlane_b32 s19, v249, 8
	v_readlane_b32 s20, v249, 9
	v_readlane_b32 s21, v249, 10
	v_readlane_b32 s28, v249, 17
	v_readlane_b32 s29, v249, 18
	v_readlane_b32 s30, v249, 19
	v_readlane_b32 s31, v249, 20
	s_ashr_i32 s1, s0, 31
	v_readlane_b32 s90, v249, 37
	v_mov_b32_e32 v95, v97
	s_mov_b32 s15, 0
	v_add_u32_e32 v140, 0, v96
	v_add_u32_e32 v142, 64, v138
	v_add_u32_e32 v143, 0x80, v138
	v_add_u32_e32 v144, 0xc0, v138
	v_add_u32_e32 v145, 0x100, v138
	v_add_u32_e32 v146, 0x140, v138
	v_add_u32_e32 v147, 0x180, v138
	v_add_u32_e32 v149, 0x1c0, v138
	v_add_u32_e32 v150, 0x200, v138
	v_add_u32_e32 v151, 0x240, v138
	v_add_u32_e32 v152, 0x280, v138
	v_add_u32_e32 v153, 0x2c0, v138
	v_add_u32_e32 v154, 0x300, v138
	v_add_u32_e32 v155, 0x340, v138
	v_add_u32_e32 v156, 0x380, v138
	v_add_u32_e32 v157, 0x3c0, v138
	v_add_u32_e32 v158, 0x400, v138
	v_add_u32_e32 v159, 0x440, v138
	v_add_u32_e32 v160, 0x480, v138
	v_add_u32_e32 v161, 0x4c0, v138
	v_add_u32_e32 v162, 0x500, v138
	v_add_u32_e32 v163, 0x540, v138
	v_add_u32_e32 v164, 0x580, v138
	v_add_u32_e32 v165, 0x5c0, v138
	v_add_u32_e32 v166, 0x600, v138
	v_add_u32_e32 v167, 0x640, v138
	v_add_u32_e32 v168, 0x680, v138
	v_add_u32_e32 v169, 0x6c0, v138
	v_add_u32_e32 v170, 0x700, v138
	v_add_u32_e32 v171, 0x740, v138
	v_add_u32_e32 v172, 0x780, v138
	v_add_u32_e32 v173, 0x7c0, v138
	v_add_u32_e32 v174, 0x800, v138
	v_add_u32_e32 v175, 0x840, v138
	v_add_u32_e32 v176, 0x880, v138
	v_add_u32_e32 v177, 0x8c0, v138
	v_add_u32_e32 v178, 0x900, v138
	v_add_u32_e32 v179, 0x940, v138
	v_add_u32_e32 v180, 0x980, v138
	v_add_u32_e32 v181, 0x9c0, v138
	v_add_u32_e32 v182, 0xa00, v138
	v_add_u32_e32 v183, 0xa40, v138
	v_add_u32_e32 v185, 0xa80, v138
	v_add_u32_e32 v187, 0xac0, v138
	v_add_u32_e32 v190, 0xb00, v138
	v_add_u32_e32 v191, 0xb40, v138
	v_add_u32_e32 v192, 0xb80, v138
	v_add_u32_e32 v193, 0xbc0, v138
	v_add_u32_e32 v194, 0xc00, v138
	v_add_u32_e32 v195, 0xc40, v138
	v_add_u32_e32 v196, 0xc80, v138
	v_add_u32_e32 v197, 0xcc0, v138
	v_add_u32_e32 v198, 0xd00, v138
	v_add_u32_e32 v199, 0xd40, v138
	v_add_u32_e32 v200, 0xd80, v138
	v_add_u32_e32 v201, 0xdc0, v138
	v_add_u32_e32 v202, 0xe00, v138
	v_add_u32_e32 v203, 0xe40, v138
	v_add_u32_e32 v204, 0xe80, v138
	v_add_u32_e32 v205, 0xec0, v138
	v_add_u32_e32 v206, 0xf00, v138
	v_add_u32_e32 v207, 0xf40, v138
	v_add_u32_e32 v208, 0xf80, v138
	v_add_u32_e32 v209, 0xfc0, v138
	v_add_u32_e32 v211, v3, v96
	v_cmp_eq_u32_e64 s[12:13], 0, v186
	v_lshl_add_u32 v212, v148, 2, 0
	v_mov_b32_e32 v93, v97
	v_lshl_add_u64 v[98:99], s[20:21], 0, v[96:97]
	v_mov_b32_e32 v101, v97
	v_lshl_add_u64 v[102:103], s[72:73], 0, v[4:5]
	s_lshl_b64 s[16:17], s[0:1], 19
	v_lshl_add_u64 v[104:105], s[84:85], 0, v[4:5]
	s_movk_i32 s3, 0x5e00
	v_lshlrev_b32_e32 v106, 1, v2
	v_mov_b32_e32 v213, 0x5000
	v_mov_b32_e32 v214, 0x1780b000
	v_mov_b32_e32 v215, 0x17811000
	v_mov_b32_e32 v216, 0x17817000
	s_movk_i32 s19, 0x2000
	v_mov_b32_e32 v217, 0xffff
	s_mov_b32 s28, 0xbfb8aa3b
	s_mov_b32 s29, 0x800000
	s_mov_b32 s30, 0x3f317217
	s_mov_b32 s31, 0x7f800000
	s_mov_b32 s18, 0x3d800000
	v_add_u32_e32 v218, v135, v1
	s_mov_b32 s34, 0xb668000
	s_mov_b32 s35, 0xb66a000
	s_mov_b32 s36, 0xb66c000
	s_mov_b32 s37, 0xb66e000
	s_mov_b32 s38, 0xb670000
	s_mov_b32 s39, 0xb672000
	s_mov_b32 s40, 0xb674000
	s_mov_b32 s41, 0xb676000
	s_mov_b32 s42, 0xb678000
	s_mov_b32 s43, 0xb67a000
	s_mov_b32 s44, 0xb67c000
	s_mov_b32 s45, 0xb67e000
	v_add_u32_e32 v219, v3, v6
	v_mov_b32_e32 v220, 0x358637bd
	v_lshlrev_b32_e32 v96, 1, v0
	s_movk_i32 s46, 0x1800
	v_mov_b32_e32 v221, 0x41b17218
	s_mov_b32 s47, s2
	v_readlane_b32 s88, v249, 39
	v_readlane_b32 s91, v249, 38
	v_readlane_b32 s22, v249, 11
	v_readlane_b32 s23, v249, 12
	v_readlane_b32 s24, v249, 13
	v_readlane_b32 s25, v249, 14
	v_readlane_b32 s26, v249, 15
	v_readlane_b32 s27, v249, 16
	v_readlane_b32 s89, v249, 40
	s_cmp_lg_u32 s100, 1
	s_cbranch_scc1 .LBB0_384
	v_mov_b32_e32 v146, v66
	v_mov_b32_e32 v147, v251
	v_mov_b32_e32 v149, v252
	v_mov_b32_e32 v182, v253
	s_branch .LBB0_392
.Lswap_g_exit:
	s_cmp_eq_u32 s100, 2
	s_cbranch_scc1 .Lswap_cont2
	s_branch .LBB0_392

; __device__ __forceinline__ unsigned xb_ld(unsigned* p)              { return __hip_atomic_load(p, __ATOMIC_RELAXED, __HIP_MEMORY_SCOPE_AGENT); }
; __device__ __forceinline__ unsigned xb_add(unsigned* p, unsigned v) { return __hip_atomic_fetch_add(p, v, __ATOMIC_RELAXED, __HIP_MEMORY_SCOPE_AGENT); }
; #define XB_SPIN(cond, bar) do { unsigned _sp = 0; while (cond) { __builtin_amdgcn_s_sleep(1); \
;     if ((++_sp & 255u) == 0u) { if (xb_ld(&(bar)[XB_TMO])) break; if (_sp > XB_SPIN_CAP) { atomicAdd(&(bar)[XB_TMO], 1u); break; } } } } while (0)
; __device__ __forceinline__ void xcd_barrier(const XcdBarrier& b) {
;     asm volatile("s_waitcnt vmcnt(0)" ::: "memory");
;     __syncthreads();
;     if (threadIdx.x == 0) {
;         unsigned* bar = b.bar;
;         __builtin_amdgcn_s_waitcnt(0);
;         unsigned nloc = b.st[0], nx = b.st[1];
;         if (nloc == 0u) { xcd_barrier_complete(bar, b.x, nloc, nx); b.st[0] = nloc; b.st[1] = nx; }
;         const unsigned old = xb_add(&bar[XB_XSUB(b.x)], 1u);
;         const unsigned gen = old / nloc;
;         if (old + 1u == (gen + 1u) * nloc) {
;             __builtin_amdgcn_fence(__ATOMIC_RELEASE, "agent");
;             asm volatile("s_waitcnt vmcnt(0)" ::: "memory");
;             const unsigned og = xb_add(&bar[XB_TOP], 1u);
;             const unsigned tg = og / nx;
;             if (og + 1u == (tg + 1u) * nx) xb_add(&bar[XB_TOPGEN], 1u);
;             else XB_SPIN(xb_ld(&bar[XB_TOPGEN]) == tg, bar);
;             __builtin_amdgcn_fence(__ATOMIC_ACQUIRE, "agent");
;             xb_add(&bar[XB_XGEN(b.x)], 1u);
;             asm volatile("s_waitcnt vmcnt(0)" ::: "memory");
;         } else {
;             XB_SPIN(xb_ld(&bar[XB_XGEN(b.x)]) == gen, bar);
;             __builtin_amdgcn_fence(__ATOMIC_ACQUIRE, "agent");
;             asm volatile("s_waitcnt vmcnt(0)" ::: "memory");
;         }
;     }
;     __syncthreads();
; }
; __global__ void __launch_bounds__(512, 2) hybrid_fwd(Args a) {
;     ...
;         xcd_barrier(xbar);
.LBB0_432:
.Lswap_cont:
	s_waitcnt vmcnt(0)
	s_barrier
	v_cmp_eq_u32_e32 vcc, 0, v188
	s_and_saveexec_b64 s[0:1], vcc
	s_cbranch_execz .Lfw_done
	v_mov_b32_e32 v0, 0
	s_add_u32 s6, s86, 0x23840
	s_addc_u32 s7, s87, 0
	v_readlane_b32 s3, v249, 21
	s_mov_b32 s12, 0x40000

; __device__ __forceinline__ void gla_prompt_unit(const Args& a, unsigned char* lds, int unit, int tid) {
;     const int lane = tid & 63, wave = tid >> 6, r16 = lane & 15, q4 = lane >> 4;
;     const int bh = unit >> 3, vs = unit & 7, b = bh >> 2, h = bh & 3;
;     unsigned char* QI = lds; unsigned char* KDT = lds + 33792; unsigned char* ST = lds + 54272;
;     unsigned char* VT = lds + 88064; unsigned char* AM = lds + 93184; float* DEC = (float*)(lds + 98304);
;     const bf16_t* Z = (const bf16_t*)(a.ws + WS_Z); bf16_t* OCAT = (bf16_t*)(a.ws + WS_OCAT); float* GSS = (float*)(a.ws + WS_GSSP);
;     const bf16_t* QIg = (const bf16_t*)(a.ws + WS_QIG); const bf16_t* KDg = (const bf16_t*)(a.ws + WS_KDG); const bf16_t* AMg = (const bf16_t*)(a.ws + WS_AMG); const float* DECg = (const float*)(a.ws + WS_DECG);
;     for (int i = tid; i < 33792 / 16; i += 512) ((u32x4*)ST)[i] = (u32x4){0u, 0u, 0u, 0u};
;     f32x4 sacc[2][4];
; #pragma unroll
;     for (int i = 0; i < 2; ++i)
; #pragma unroll
; __device__ __forceinline__ void xcd_barrier(const XcdBarrier& b) {
;     asm volatile("s_waitcnt vmcnt(0)" ::: "memory");
;     __syncthreads();
;     if (threadIdx.x == 0) {
;         unsigned* bar = b.bar;
;         __builtin_amdgcn_s_waitcnt(0);
;         unsigned nloc = b.st[0], nx = b.st[1];
;         if (nloc == 0u) { xcd_barrier_complete(bar, b.x, nloc, nx); b.st[0] = nloc; b.st[1] = nx; }
;         const unsigned old = xb_add(&bar[XB_XSUB(b.x)], 1u);
;         const unsigned gen = old / nloc;
;         if (old + 1u == (gen + 1u) * nloc) {
;             __builtin_amdgcn_fence(__ATOMIC_RELEASE, "agent");
;             asm volatile("s_waitcnt vmcnt(0)" ::: "memory");
;             const unsigned og = xb_add(&bar[XB_TOP], 1u);
;             const unsigned tg = og / nx;
;             if (og + 1u == (tg + 1u) * nx) xb_add(&bar[XB_TOPGEN], 1u);
;             else XB_SPIN(xb_ld(&bar[XB_TOPGEN]) == tg, bar);
;             __builtin_amdgcn_fence(__ATOMIC_ACQUIRE, "agent");
;             xb_add(&bar[XB_XGEN(b.x)], 1u);
;             asm volatile("s_waitcnt vmcnt(0)" ::: "memory");
;         } else {
;             XB_SPIN(xb_ld(&bar[XB_XGEN(b.x)]) == gen, bar);
;             __builtin_amdgcn_fence(__ATOMIC_ACQUIRE, "agent");
;             asm volatile("s_waitcnt vmcnt(0)" ::: "memory");
;         }
;     }
;     __syncthreads();
; }
.Lfw_done:
.LBB0_484:
	s_or_b64 exec, exec, s[0:1]
	s_cmpk_gt_i32 s33, 0xff
	s_movk_i32 s0, 0xff
	s_waitcnt lgkmcnt(0)
	s_barrier
	s_cbranch_scc1 .LBB0_521
	v_mov_b32_e32 v0, 0
	v_lshlrev_b32_e32 v70, 4, v188
	v_mov_b32_e32 v71, v0
	v_lshl_add_u64 v[6:7], s[86:87], 0, v[70:71]
	s_mov_b64 s[8:9], 0x2f100000
	v_lshl_add_u64 v[72:73], v[6:7], 0, s[8:9]
	v_lshrrev_b32_e32 v6, 2, v188
	v_mov_b32_e32 v7, 0x3fffffc0
	v_and_or_b32 v76, v6, 56, v7
	v_add_u32_e32 v7, 0xffffff00, v188
	v_cmp_lt_u32_e64 s[8:9], s0, v188
	s_movk_i32 s0, 0x100
	v_lshrrev_b32_e32 v7, 2, v7
	v_cmp_gt_u32_e64 s[10:11], s0, v188
	v_and_b32_e32 v78, 0x3ffffff8, v7
	v_and_b32_e32 v7, 0x1f0, v70
	s_add_i32 s0, 0, 0x16c00
	v_add_u32_e32 v11, 0, v7
	s_movk_i32 s3, 0x50
	v_mov_b32_e32 v7, s0
	s_add_i32 s0, 0, 0x18000
	v_mul_u32_u24_e32 v13, 0x50, v6
	v_mad_u32_u24 v77, v6, s3, v7
	v_add_u32_e32 v6, s0, v70
	v_add_u32_e32 v79, 0xfffff800, v6
	v_bfe_u32 v6, v188, 6, 2
	v_lshlrev_b32_e32 v2, 1, v91
	v_mov_b32_e32 v3, v0
	v_lshlrev_b32_e32 v8, 4, v6
	v_lshl_add_u64 v[4:5], s[86:87], 0, v[2:3]
	v_and_b32_e32 v74, 31, v188
	s_add_i32 s14, 0, 0x15800
	v_or_b32_e32 v14, v8, v124
	s_movk_i32 s15, 0x210
	v_and_b32_e32 v16, 48, v188
	v_and_or_b32 v80, v126, 48, v124
	v_mov_b32_e32 v27, 0x4200
	v_lshl_add_u64 v[82:83], s[76:77], 0, v[2:3]
	v_add_u32_e32 v2, 0, v70
	v_mov_b32_e32 v10, s14
	v_lshl_add_u32 v81, v74, 1, s14
	v_mad_u32_u24 v15, v14, s15, 0
	v_mad_u32_u24 v17, v80, s15, 0
	v_add_u32_e32 v21, s14, v16
	v_mad_u32_u24 v27, v124, s15, v27
	s_mov_b64 s[14:15], 0x2cd00000
	v_add_u32_e32 v123, 0xd400, v2
	s_movk_i32 s40, 0x5e00
	v_mov_b64_e32 v[2:3], 0xc6bdc00
	v_and_b32_e32 v19, 48, v186
	v_mul_u32_u24_e32 v22, 0x210, v87
	v_mul_u32_u24_e32 v23, 0x210, v84
	v_lshl_add_u64 v[84:85], v[4:5], 0, s[14:15]
	v_mad_u64_u32 v[86:87], s[14:15], v74, s40, v[2:3]
	v_lshrrev_b32_e32 v1, 4, v186
	s_mov_b64 s[6:7], 0x2ed00000
	v_mad_u32_u24 v18, v80, s3, v7
	v_lshlrev_b32_e32 v7, 5, v148
	v_add3_u32 v114, s0, v19, v125
	s_mov_b64 s[14:15], 0x2ed00800
	v_lshlrev_b32_e32 v2, 9, v80
	v_lshlrev_b32_e32 v3, 2, v6
	s_mov_b32 s0, 0x33700000
	v_lshl_add_u64 v[68:69], v[4:5], 0, s[6:7]
	v_mad_u32_u24 v14, v14, s3, v10
	v_lshlrev_b32_e32 v10, 2, v1
	v_lshrrev_b32_e32 v24, 2, v89
	v_or_b32_e32 v19, v7, v124
	v_lshl_add_u64 v[88:89], v[70:71], 0, s[14:15]
	s_mov_b64 s[14:15], 0x2f0ffc00
	v_or3_b32 v92, v2, v3, s0
	v_mul_u32_u24_e32 v2, 0x1800, v80
	v_lshlrev_b32_e32 v4, 5, v6
	v_lshrrev_b32_e32 v5, 1, v16
	s_movk_i32 s1, 0x80
	v_and_b32_e32 v9, 0x3c0, v188
	v_and_b32_e32 v75, 48, v70
	v_mul_u32_u24_e32 v26, 0x50, v19
	v_or_b32_e32 v19, 16, v19
	v_lshlrev_b32_e32 v1, 3, v1
	v_or_b32_e32 v7, v10, v7
	v_lshl_add_u64 v[90:91], v[70:71], 0, s[14:15]
	v_mul_hi_u32_u24_e32 v3, 0x1800, v80
	v_or3_b32 v2, v2, v4, v5
	s_mov_b64 s[14:15], 0x24a00800
	v_cmp_eq_u32_e64 s[6:7], s1, v9
	v_add_u32_e32 v12, 0, v75
	v_add_u32_e32 v20, 0, v16
	v_mul_u32_u24_e32 v24, 0x50, v24
	v_mul_u32_u24_e32 v25, 0x50, v124
	v_mul_u32_u24_e32 v19, 0x50, v19
	v_add3_u32 v1, 0, v9, v1
	v_mul_u32_u24_e32 v9, 0x210, v124
	s_add_u32 s38, s84, 0x8600000
	v_lshlrev_b32_e32 v115, 9, v7
	v_lshl_add_u64 v[94:95], v[2:3], 0, s[14:15]
	v_mbcnt_lo_u32_b32 v2, -1, 0
	v_readlane_b32 s52, v249, 33
	v_cmp_gt_u32_e64 s[4:5], s1, v188
	s_mov_b32 s1, 0
	v_cmp_gt_u32_e64 s[12:13], 16, v186
	s_addc_u32 s39, s85, 0
	v_or_b32_e32 v116, 0x200, v115
	v_or_b32_e32 v117, 0x400, v115
	v_or_b32_e32 v118, 0x600, v115
	v_or_b32_e32 v119, 0x2000, v115
	v_or_b32_e32 v120, 0x2200, v115
	v_or_b32_e32 v121, 0x2400, v115
	v_or_b32_e32 v122, 0x2600, v115
	v_add_u32_e32 v125, 0xfffffe00, v188
	v_mov_b32_e32 v93, v0
	s_movk_i32 s41, 0x1800
	s_movk_i32 s42, 0x63f
	s_mov_b64 s[14:15], 0xbc000
	s_mov_b64 s[16:17], 0x800
	s_mov_b64 s[18:19], 0x400
	s_mov_b64 s[20:21], 0x4000
	s_mov_b64 s[22:23], 0x30000
	s_mov_b64 s[24:25], 0x7e0
	v_lshlrev_b32_e32 v96, 1, v8
	v_lshlrev_b32_e32 v98, 1, v10
	s_mov_b32 s43, 0x24a00000
	v_lshlrev_b32_e32 v100, 2, v6
	v_mov_b32_e32 v4, 0
	v_mov_b32_e32 v5, v0
	v_mov_b32_e32 v6, v0
	v_mov_b32_e32 v7, v0
	v_mov_b32_e32 v71, 0x5e00
	v_add_u32_e32 v126, v11, v22
	v_add_u32_e32 v127, v12, v13
	v_add_u32_e32 v128, v11, v23
	v_add_u32_e32 v129, v12, v24
	v_add_u32_e32 v130, v15, v16
	v_add_u32_e32 v131, v17, v16
	v_add_u32_e32 v132, v14, v16
	v_add_u32_e32 v133, v18, v16
	v_mbcnt_hi_u32_b32 v134, -1, v2
	v_add_u32_e32 v135, v20, v26
	v_add_u32_e32 v136, v21, v25
	v_add_u32_e32 v137, v20, v19
	v_add_u32_e32 v138, v1, v9
	v_add_u32_e32 v139, v1, v27
	s_mov_b32 s44, s33
	v_readlane_b32 s53, v249, 34
	s_branch .LBB0_487

; __global__ void __launch_bounds__(512, 2) hybrid_fwd(Args a) {
;     ...
;         for (int u = bx; u < 512; u += G) gla_sample_unit(a, lds, u, tid);
;         for (int u = bx; u < 512; u += G) swa_sample_unit(a, lds, u, tid);
;         xcd_barrier(xbar);
;         for (int u = vcu; u < 256; u += G) gla_prompt_unit(a, lds, u, tid);
.LBB0_521:
	s_cmp_eq_u32 s100, 1
	s_cbranch_scc0 .Lswap_cont2
	s_mov_b32 s100, 2
	v_mov_b32_e32 v66, v146
	s_waitcnt vmcnt(0) lgkmcnt(0)
	s_barrier
	s_branch .LBB0_382
